# grid-barrier spin loops: s_sleep 1 -> s_sleep 3 (fewer polls while stragglers finish)
# baseline (speedup 1.0000x reference)
.LBB0_184:
	s_sleep 3
	global_load_dword v2, v0, s[2:3] offset:32 sc1
	s_waitcnt vmcnt(0)
	v_and_b32_e32 v2, 0xffff0000, v2
	v_cmp_ne_u32_e32 vcc, v2, v1
	s_or_b64 s[4:5], vcc, s[4:5]
	s_andn2_b64 exec, exec, s[4:5]
	s_cbranch_execnz .LBB0_184

; __device__ __forceinline__ unsigned xb_ld(unsigned* p)              { return __hip_atomic_load(p, __ATOMIC_RELAXED, __HIP_MEMORY_SCOPE_AGENT); }
; __device__ __forceinline__ void xcd_barrier_complete(unsigned* bar, unsigned x, unsigned& nloc, unsigned& nx) {
;     const unsigned G = gridDim.x * gridDim.y * gridDim.z;
;     unsigned sum, cnt, mine, sp = 0u;
;     for (;;) {
;         sum = 0u; cnt = 0u; mine = 0u;
; #pragma unroll
;         for (unsigned j = 0; j < 16; ++j) { const unsigned c = xb_ld(&bar[XB_XCNT(j)]); sum += c; cnt += (c > 0u) ? 1u : 0u; mine = (j == x) ? c : mine; }
;         if (sum == G) break;
;         __builtin_amdgcn_s_sleep(1);
;         if ((++sp & 255u) == 0u) { if (xb_ld(&bar[XB_TMO])) break; if (sp > XB_SPIN_CAP) { atomicAdd(&bar[XB_TMO], 1u); break; } }
;     }
;     nloc = mine > 0u ? mine : 1u; nx = cnt > 0u ? cnt : 1u;
; }
.LBB0_217:
	global_load_dword v15, v16, s[10:11] offset:1024 sc1
	s_waitcnt lgkmcnt(0)
	global_load_dword v0, v16, s[10:11] offset:1280 sc1
	global_load_dword v1, v16, s[10:11] offset:1536 sc1
	global_load_dword v2, v16, s[10:11] offset:1792 sc1
	global_load_dword v3, v16, s[10:11] offset:2048 sc1
	global_load_dword v4, v16, s[10:11] offset:2304 sc1
	global_load_dword v5, v16, s[10:11] offset:2560 sc1
	global_load_dword v6, v16, s[10:11] offset:2816 sc1
	global_load_dword v7, v16, s[10:11] offset:3072 sc1
	global_load_dword v8, v16, s[10:11] offset:3328 sc1
	global_load_dword v9, v16, s[10:11] offset:3584 sc1
	global_load_dword v10, v16, s[10:11] offset:3840 sc1
	global_load_dword v11, v16, s[2:3] sc1
	global_load_dword v12, v16, s[4:5] sc1
	global_load_dword v13, v16, s[6:7] sc1
	global_load_dword v14, v16, s[14:15] sc1
	s_mov_b64 s[16:17], -1
	s_mov_b64 s[18:19], -1
	s_waitcnt vmcnt(14)
	v_add_u32_e32 v17, v0, v15
	s_waitcnt vmcnt(13)
	v_add_u32_e32 v17, v17, v1
	s_waitcnt vmcnt(12)
	v_add_u32_e32 v17, v17, v2
	s_waitcnt vmcnt(11)
	v_add_u32_e32 v17, v17, v3
	s_waitcnt vmcnt(10)
	v_add_u32_e32 v17, v17, v4
	s_waitcnt vmcnt(9)
	v_add_u32_e32 v17, v17, v5
	s_waitcnt vmcnt(8)
	v_add_u32_e32 v17, v17, v6
	s_waitcnt vmcnt(7)
	v_add_u32_e32 v17, v17, v7
	s_waitcnt vmcnt(6)
	v_add_u32_e32 v17, v17, v8
	s_waitcnt vmcnt(5)
	v_add_u32_e32 v17, v17, v9
	s_waitcnt vmcnt(4)
	v_add_u32_e32 v17, v17, v10
	s_waitcnt vmcnt(3)
	v_add_u32_e32 v17, v17, v11
	s_waitcnt vmcnt(2)
	v_add_u32_e32 v17, v17, v12
	s_waitcnt vmcnt(1)
	v_add_u32_e32 v17, v17, v13
	s_waitcnt vmcnt(0)
	v_add_u32_e32 v17, v17, v14
	v_cmp_eq_u32_e32 vcc, s22, v17
	s_cbranch_vccnz .LBB0_216
	s_and_b32 s16, s23, 0xff
	s_cmp_eq_u32 s16, 0
	s_mov_b64 s[16:17], -1
	s_mov_b64 s[20:21], -1
	s_sleep 3
	s_cbranch_scc0 .LBB0_221
	global_load_dword v17, v16, s[10:11] offset:512 sc1
	s_waitcnt vmcnt(0)
	v_cmp_eq_u32_e32 vcc, 0, v17
	s_cbranch_vccnz .LBB0_223
	s_mov_b64 s[20:21], 0

; __device__ __forceinline__ unsigned xb_ld(unsigned* p)              { return __hip_atomic_load(p, __ATOMIC_RELAXED, __HIP_MEMORY_SCOPE_AGENT); }
; __device__ __forceinline__ unsigned xb_add(unsigned* p, unsigned v) { return __hip_atomic_fetch_add(p, v, __ATOMIC_RELAXED, __HIP_MEMORY_SCOPE_AGENT); }
; #define XB_SPIN(cond, bar) do { unsigned _sp = 0; while (cond) { __builtin_amdgcn_s_sleep(1); \
;     if ((++_sp & 255u) == 0u) { if (xb_ld(&(bar)[XB_TMO])) break; if (_sp > XB_SPIN_CAP) { atomicAdd(&(bar)[XB_TMO], 1u); break; } } } } while (0)
; __device__ __forceinline__ void xcd_barrier(const XcdBarrier& b, const int wv) {
;     ...
;         if (old + 1u == (gen + 1u) * nloc) {
;             __builtin_amdgcn_fence(__ATOMIC_RELEASE, "agent");
;             asm volatile("s_waitcnt vmcnt(0)" ::: "memory");
;             const unsigned og = xb_add(&bar[XB_TOP], 1u);
;             const unsigned tg = og / nx;
;             if (og + 1u == (tg + 1u) * nx) xb_add(&bar[XB_TOPGEN], 1u);
;             else XB_SPIN(xb_ld(&bar[XB_TOPGEN]) == tg, bar);
;             __builtin_amdgcn_fence(__ATOMIC_ACQUIRE, "agent");
;             xb_add(&bar[XB_XGEN(b.x)], 1u);
;             asm volatile("s_waitcnt vmcnt(0)" ::: "memory");
;         } else {
;             XB_SPIN(xb_ld(&bar[XB_XGEN(b.x)]) == gen, bar);
.LBB0_235:
	s_and_b32 s22, s29, 0xff
	s_mov_b64 s[20:21], -1
	s_cmp_lg_u32 s22, 0
	s_mov_b64 s[36:37], -1
	s_sleep 3
	s_cbranch_scc1 .LBB0_238
	global_load_dword v2, v0, s[10:11] offset:512 sc1
	s_waitcnt vmcnt(0)
	v_cmp_eq_u32_e32 vcc, 0, v2
	s_cbranch_vccnz .LBB0_240
	s_mov_b64 s[36:37], 0
	s_mov_b64 s[22:23], -1

; __device__ __forceinline__ unsigned xb_ld(unsigned* p)              { return __hip_atomic_load(p, __ATOMIC_RELAXED, __HIP_MEMORY_SCOPE_AGENT); }
; __device__ __forceinline__ unsigned xb_add(unsigned* p, unsigned v) { return __hip_atomic_fetch_add(p, v, __ATOMIC_RELAXED, __HIP_MEMORY_SCOPE_AGENT); }
; #define XB_SPIN(cond, bar) do { unsigned _sp = 0; while (cond) { __builtin_amdgcn_s_sleep(1); \
;     if ((++_sp & 255u) == 0u) { if (xb_ld(&(bar)[XB_TMO])) break; if (_sp > XB_SPIN_CAP) { atomicAdd(&(bar)[XB_TMO], 1u); break; } } } } while (0)
; __device__ __forceinline__ void xcd_barrier(const XcdBarrier& b, const int wv) {
;     ...
;         if (old + 1u == (gen + 1u) * nloc) {
;             __builtin_amdgcn_fence(__ATOMIC_RELEASE, "agent");
;             asm volatile("s_waitcnt vmcnt(0)" ::: "memory");
;             const unsigned og = xb_add(&bar[XB_TOP], 1u);
;             const unsigned tg = og / nx;
;             if (og + 1u == (tg + 1u) * nx) xb_add(&bar[XB_TOPGEN], 1u);
;             else XB_SPIN(xb_ld(&bar[XB_TOPGEN]) == tg, bar);
;             __builtin_amdgcn_fence(__ATOMIC_ACQUIRE, "agent");
;             xb_add(&bar[XB_XGEN(b.x)], 1u);
;             asm volatile("s_waitcnt vmcnt(0)" ::: "memory");
;         } else {
;             XB_SPIN(xb_ld(&bar[XB_XGEN(b.x)]) == gen, bar);
.LBB0_252:
	s_and_b32 s22, s29, 0xff
	s_cmp_lg_u32 s22, 0
	s_mov_b64 s[36:37], -1
	s_sleep 3
	s_cbranch_scc1 .LBB0_255
	global_load_dword v1, v0, s[14:15] sc1
	s_waitcnt vmcnt(0)
	v_cmp_eq_u32_e32 vcc, 0, v1
	s_cbranch_vccnz .LBB0_257
	s_mov_b64 s[36:37], 0
	s_mov_b64 s[22:23], -1

; __device__ __forceinline__ unsigned xb_ld(unsigned* p)              { return __hip_atomic_load(p, __ATOMIC_RELAXED, __HIP_MEMORY_SCOPE_AGENT); }
; __device__ __forceinline__ void xcd_barrier_complete(unsigned* bar, unsigned x, unsigned& nloc, unsigned& nx) {
;     const unsigned G = gridDim.x * gridDim.y * gridDim.z;
;     unsigned sum, cnt, mine, sp = 0u;
;     for (;;) {
;         sum = 0u; cnt = 0u; mine = 0u;
; #pragma unroll
;         for (unsigned j = 0; j < 16; ++j) { const unsigned c = xb_ld(&bar[XB_XCNT(j)]); sum += c; cnt += (c > 0u) ? 1u : 0u; mine = (j == x) ? c : mine; }
;         if (sum == G) break;
;         __builtin_amdgcn_s_sleep(1);
;         if ((++sp & 255u) == 0u) { if (xb_ld(&bar[XB_TMO])) break; if (sp > XB_SPIN_CAP) { atomicAdd(&bar[XB_TMO], 1u); break; } }
;     }
;     nloc = mine > 0u ? mine : 1u; nx = cnt > 0u ? cnt : 1u;
; }
.LBB0_286:
	global_load_dword v15, v16, s[10:11] offset:1024 sc1
	s_waitcnt lgkmcnt(0)
	global_load_dword v0, v16, s[10:11] offset:1280 sc1
	global_load_dword v1, v16, s[10:11] offset:1536 sc1
	global_load_dword v2, v16, s[10:11] offset:1792 sc1
	global_load_dword v3, v16, s[10:11] offset:2048 sc1
	global_load_dword v4, v16, s[10:11] offset:2304 sc1
	global_load_dword v5, v16, s[10:11] offset:2560 sc1
	global_load_dword v6, v16, s[10:11] offset:2816 sc1
	global_load_dword v7, v16, s[10:11] offset:3072 sc1
	global_load_dword v8, v16, s[10:11] offset:3328 sc1
	global_load_dword v9, v16, s[10:11] offset:3584 sc1
	global_load_dword v10, v16, s[10:11] offset:3840 sc1
	global_load_dword v11, v16, s[2:3] sc1
	global_load_dword v12, v16, s[4:5] sc1
	global_load_dword v13, v16, s[6:7] sc1
	global_load_dword v14, v16, s[20:21] sc1
	s_mov_b64 s[22:23], -1
	s_mov_b64 s[36:37], -1
	s_waitcnt vmcnt(14)
	v_add_u32_e32 v17, v0, v15
	s_waitcnt vmcnt(13)
	v_add_u32_e32 v17, v17, v1
	s_waitcnt vmcnt(12)
	v_add_u32_e32 v17, v17, v2
	s_waitcnt vmcnt(11)
	v_add_u32_e32 v17, v17, v3
	s_waitcnt vmcnt(10)
	v_add_u32_e32 v17, v17, v4
	s_waitcnt vmcnt(9)
	v_add_u32_e32 v17, v17, v5
	s_waitcnt vmcnt(8)
	v_add_u32_e32 v17, v17, v6
	s_waitcnt vmcnt(7)
	v_add_u32_e32 v17, v17, v7
	s_waitcnt vmcnt(6)
	v_add_u32_e32 v17, v17, v8
	s_waitcnt vmcnt(5)
	v_add_u32_e32 v17, v17, v9
	s_waitcnt vmcnt(4)
	v_add_u32_e32 v17, v17, v10
	s_waitcnt vmcnt(3)
	v_add_u32_e32 v17, v17, v11
	s_waitcnt vmcnt(2)
	v_add_u32_e32 v17, v17, v12
	s_waitcnt vmcnt(1)
	v_add_u32_e32 v17, v17, v13
	s_waitcnt vmcnt(0)
	v_add_u32_e32 v17, v17, v14
	v_cmp_eq_u32_e32 vcc, s29, v17
	s_cbranch_vccnz .LBB0_285
	s_and_b32 s22, s31, 0xff
	s_cmp_eq_u32 s22, 0
	s_mov_b64 s[22:23], -1
	s_mov_b64 s[38:39], -1
	s_sleep 3
	s_cbranch_scc0 .LBB0_290
	global_load_dword v17, v16, s[10:11] offset:512 sc1
	s_waitcnt vmcnt(0)
	v_cmp_eq_u32_e32 vcc, 0, v17
	s_cbranch_vccnz .LBB0_292
	s_mov_b64 s[38:39], 0

; __device__ __forceinline__ unsigned xb_ld(unsigned* p)              { return __hip_atomic_load(p, __ATOMIC_RELAXED, __HIP_MEMORY_SCOPE_AGENT); }
; __device__ __forceinline__ unsigned xb_add(unsigned* p, unsigned v) { return __hip_atomic_fetch_add(p, v, __ATOMIC_RELAXED, __HIP_MEMORY_SCOPE_AGENT); }
; #define XB_SPIN(cond, bar) do { unsigned _sp = 0; while (cond) { __builtin_amdgcn_s_sleep(1); \
;     if ((++_sp & 255u) == 0u) { if (xb_ld(&(bar)[XB_TMO])) break; if (_sp > XB_SPIN_CAP) { atomicAdd(&(bar)[XB_TMO], 1u); break; } } } } while (0)
; __device__ __forceinline__ void xcd_barrier(const XcdBarrier& b, const int wv) {
;     ...
;         if (old + 1u == (gen + 1u) * nloc) {
;             __builtin_amdgcn_fence(__ATOMIC_RELEASE, "agent");
;             asm volatile("s_waitcnt vmcnt(0)" ::: "memory");
;             const unsigned og = xb_add(&bar[XB_TOP], 1u);
;             const unsigned tg = og / nx;
;             if (og + 1u == (tg + 1u) * nx) xb_add(&bar[XB_TOPGEN], 1u);
;             else XB_SPIN(xb_ld(&bar[XB_TOPGEN]) == tg, bar);
;             __builtin_amdgcn_fence(__ATOMIC_ACQUIRE, "agent");
;             xb_add(&bar[XB_XGEN(b.x)], 1u);
;             asm volatile("s_waitcnt vmcnt(0)" ::: "memory");
;         } else {
;             XB_SPIN(xb_ld(&bar[XB_XGEN(b.x)]) == gen, bar);
.LBB0_304:
	s_and_b32 s31, s29, 0xff
	s_mov_b64 s[38:39], -1
	s_cmp_lg_u32 s31, 0
	s_mov_b64 s[42:43], -1
	s_sleep 3
	s_cbranch_scc1 .LBB0_307
	global_load_dword v2, v0, s[10:11] offset:512 sc1
	s_waitcnt vmcnt(0)
	v_cmp_eq_u32_e32 vcc, 0, v2
	s_cbranch_vccnz .LBB0_309
	s_mov_b64 s[42:43], 0
	s_mov_b64 s[40:41], -1

; __device__ __forceinline__ unsigned xb_ld(unsigned* p)              { return __hip_atomic_load(p, __ATOMIC_RELAXED, __HIP_MEMORY_SCOPE_AGENT); }
; __device__ __forceinline__ unsigned xb_add(unsigned* p, unsigned v) { return __hip_atomic_fetch_add(p, v, __ATOMIC_RELAXED, __HIP_MEMORY_SCOPE_AGENT); }
; #define XB_SPIN(cond, bar) do { unsigned _sp = 0; while (cond) { __builtin_amdgcn_s_sleep(1); \
;     if ((++_sp & 255u) == 0u) { if (xb_ld(&(bar)[XB_TMO])) break; if (_sp > XB_SPIN_CAP) { atomicAdd(&(bar)[XB_TMO], 1u); break; } } } } while (0)
; __device__ __forceinline__ void xcd_barrier(const XcdBarrier& b, const int wv) {
;     ...
;         if (old + 1u == (gen + 1u) * nloc) {
;             __builtin_amdgcn_fence(__ATOMIC_RELEASE, "agent");
;             asm volatile("s_waitcnt vmcnt(0)" ::: "memory");
;             const unsigned og = xb_add(&bar[XB_TOP], 1u);
;             const unsigned tg = og / nx;
;             if (og + 1u == (tg + 1u) * nx) xb_add(&bar[XB_TOPGEN], 1u);
;             else XB_SPIN(xb_ld(&bar[XB_TOPGEN]) == tg, bar);
;             __builtin_amdgcn_fence(__ATOMIC_ACQUIRE, "agent");
;             xb_add(&bar[XB_XGEN(b.x)], 1u);
;             asm volatile("s_waitcnt vmcnt(0)" ::: "memory");
;         } else {
;             XB_SPIN(xb_ld(&bar[XB_XGEN(b.x)]) == gen, bar);
.LBB0_321:
	s_and_b32 s31, s29, 0xff
	s_cmp_lg_u32 s31, 0
	s_mov_b64 s[42:43], -1
	s_sleep 3
	s_cbranch_scc1 .LBB0_324
	global_load_dword v1, v0, s[20:21] sc1
	s_waitcnt vmcnt(0)
	v_cmp_eq_u32_e32 vcc, 0, v1
	s_cbranch_vccnz .LBB0_326
	s_mov_b64 s[42:43], 0
	s_mov_b64 s[40:41], -1

; __device__ __forceinline__ unsigned xb_ld(unsigned* p)              { return __hip_atomic_load(p, __ATOMIC_RELAXED, __HIP_MEMORY_SCOPE_AGENT); }
; __device__ __forceinline__ void xcd_barrier_complete(unsigned* bar, unsigned x, unsigned& nloc, unsigned& nx) {
;     const unsigned G = gridDim.x * gridDim.y * gridDim.z;
;     unsigned sum, cnt, mine, sp = 0u;
;     for (;;) {
;         sum = 0u; cnt = 0u; mine = 0u;
; #pragma unroll
;         for (unsigned j = 0; j < 16; ++j) { const unsigned c = xb_ld(&bar[XB_XCNT(j)]); sum += c; cnt += (c > 0u) ? 1u : 0u; mine = (j == x) ? c : mine; }
;         if (sum == G) break;
;         __builtin_amdgcn_s_sleep(1);
;         if ((++sp & 255u) == 0u) { if (xb_ld(&bar[XB_TMO])) break; if (sp > XB_SPIN_CAP) { atomicAdd(&bar[XB_TMO], 1u); break; } }
;     }
;     nloc = mine > 0u ? mine : 1u; nx = cnt > 0u ? cnt : 1u;
; }
.LBB0_416:
	global_load_dword v15, v16, s[10:11] offset:1024 sc1
	s_waitcnt lgkmcnt(0)
	global_load_dword v0, v16, s[10:11] offset:1280 sc1
	global_load_dword v1, v16, s[10:11] offset:1536 sc1
	global_load_dword v2, v16, s[10:11] offset:1792 sc1
	global_load_dword v3, v16, s[10:11] offset:2048 sc1
	global_load_dword v4, v16, s[10:11] offset:2304 sc1
	global_load_dword v5, v16, s[10:11] offset:2560 sc1
	global_load_dword v6, v16, s[10:11] offset:2816 sc1
	global_load_dword v7, v16, s[10:11] offset:3072 sc1
	global_load_dword v8, v16, s[10:11] offset:3328 sc1
	global_load_dword v9, v16, s[10:11] offset:3584 sc1
	global_load_dword v10, v16, s[10:11] offset:3840 sc1
	global_load_dword v11, v16, s[2:3] sc1
	global_load_dword v12, v16, s[4:5] sc1
	global_load_dword v13, v16, s[6:7] sc1
	global_load_dword v14, v16, s[20:21] sc1
	s_mov_b64 s[22:23], -1
	s_mov_b64 s[36:37], -1
	s_waitcnt vmcnt(14)
	v_add_u32_e32 v17, v0, v15
	s_waitcnt vmcnt(13)
	v_add_u32_e32 v17, v17, v1
	s_waitcnt vmcnt(12)
	v_add_u32_e32 v17, v17, v2
	s_waitcnt vmcnt(11)
	v_add_u32_e32 v17, v17, v3
	s_waitcnt vmcnt(10)
	v_add_u32_e32 v17, v17, v4
	s_waitcnt vmcnt(9)
	v_add_u32_e32 v17, v17, v5
	s_waitcnt vmcnt(8)
	v_add_u32_e32 v17, v17, v6
	s_waitcnt vmcnt(7)
	v_add_u32_e32 v17, v17, v7
	s_waitcnt vmcnt(6)
	v_add_u32_e32 v17, v17, v8
	s_waitcnt vmcnt(5)
	v_add_u32_e32 v17, v17, v9
	s_waitcnt vmcnt(4)
	v_add_u32_e32 v17, v17, v10
	s_waitcnt vmcnt(3)
	v_add_u32_e32 v17, v17, v11
	s_waitcnt vmcnt(2)
	v_add_u32_e32 v17, v17, v12
	s_waitcnt vmcnt(1)
	v_add_u32_e32 v17, v17, v13
	s_waitcnt vmcnt(0)
	v_add_u32_e32 v17, v17, v14
	v_cmp_eq_u32_e32 vcc, s29, v17
	s_cbranch_vccnz .LBB0_415
	s_and_b32 s22, s31, 0xff
	s_cmp_eq_u32 s22, 0
	s_mov_b64 s[22:23], -1
	s_mov_b64 s[40:41], -1
	s_sleep 3
	s_cbranch_scc0 .LBB0_420
	global_load_dword v17, v16, s[10:11] offset:512 sc1
	s_waitcnt vmcnt(0)
	v_cmp_eq_u32_e32 vcc, 0, v17
	s_cbranch_vccnz .LBB0_422
	s_mov_b64 s[40:41], 0

; __device__ __forceinline__ unsigned xb_ld(unsigned* p)              { return __hip_atomic_load(p, __ATOMIC_RELAXED, __HIP_MEMORY_SCOPE_AGENT); }
; #define XB_SPIN(cond, bar) do { unsigned _sp = 0; while (cond) { __builtin_amdgcn_s_sleep(1); \
;     if ((++_sp & 255u) == 0u) { if (xb_ld(&(bar)[XB_TMO])) break; if (_sp > XB_SPIN_CAP) { atomicAdd(&(bar)[XB_TMO], 1u); break; } } } } while (0)
; __device__ __forceinline__ void xcd_barrier(const XcdBarrier& b, const int wv) {
;     ...
;             else XB_SPIN(xb_ld(&bar[XB_TOPGEN]) == tg, bar);
.LBB0_434:
	s_and_b32 s31, s29, 0xff
	s_mov_b64 s[40:41], -1
	s_cmp_lg_u32 s31, 0
	s_mov_b64 s[46:47], -1
	s_sleep 3
	s_cbranch_scc1 .LBB0_437
	global_load_dword v2, v0, s[10:11] offset:512 sc1
	s_waitcnt vmcnt(0)
	v_cmp_eq_u32_e32 vcc, 0, v2
	s_cbranch_vccnz .LBB0_439
	s_mov_b64 s[46:47], 0
	s_mov_b64 s[42:43], -1

; __device__ __forceinline__ unsigned xb_ld(unsigned* p)              { return __hip_atomic_load(p, __ATOMIC_RELAXED, __HIP_MEMORY_SCOPE_AGENT); }
; #define XB_SPIN(cond, bar) do { unsigned _sp = 0; while (cond) { __builtin_amdgcn_s_sleep(1); \
;     if ((++_sp & 255u) == 0u) { if (xb_ld(&(bar)[XB_TMO])) break; if (_sp > XB_SPIN_CAP) { atomicAdd(&(bar)[XB_TMO], 1u); break; } } } } while (0)
; __device__ __forceinline__ void xcd_barrier(const XcdBarrier& b, const int wv) {
;     ...
;             XB_SPIN(xb_ld(&bar[XB_XGEN(b.x)]) == gen, bar);
.LBB0_451:
	s_and_b32 s31, s29, 0xff
	s_cmp_lg_u32 s31, 0
	s_mov_b64 s[46:47], -1
	s_sleep 3
	s_cbranch_scc1 .LBB0_454
	global_load_dword v1, v0, s[20:21] sc1
	s_waitcnt vmcnt(0)
	v_cmp_eq_u32_e32 vcc, 0, v1
	s_cbranch_vccnz .LBB0_456
	s_mov_b64 s[46:47], 0
	s_mov_b64 s[42:43], -1

; __device__ __forceinline__ unsigned xb_ld(unsigned* p)              { return __hip_atomic_load(p, __ATOMIC_RELAXED, __HIP_MEMORY_SCOPE_AGENT); }
; __device__ __forceinline__ void xcd_barrier_complete(unsigned* bar, unsigned x, unsigned& nloc, unsigned& nx) {
;     const unsigned G = gridDim.x * gridDim.y * gridDim.z;
;     unsigned sum, cnt, mine, sp = 0u;
;     for (;;) {
;         sum = 0u; cnt = 0u; mine = 0u;
; #pragma unroll
;         for (unsigned j = 0; j < 16; ++j) { const unsigned c = xb_ld(&bar[XB_XCNT(j)]); sum += c; cnt += (c > 0u) ? 1u : 0u; mine = (j == x) ? c : mine; }
;         if (sum == G) break;
;         __builtin_amdgcn_s_sleep(1);
;         if ((++sp & 255u) == 0u) { if (xb_ld(&bar[XB_TMO])) break; if (sp > XB_SPIN_CAP) { atomicAdd(&bar[XB_TMO], 1u); break; } }
;     }
;     nloc = mine > 0u ? mine : 1u; nx = cnt > 0u ? cnt : 1u;
; }
.LBB0_655:
	global_load_dword v15, v16, s[10:11] offset:1024 sc1
	s_waitcnt lgkmcnt(0)
	global_load_dword v0, v16, s[10:11] offset:1280 sc1
	global_load_dword v1, v16, s[10:11] offset:1536 sc1
	global_load_dword v2, v16, s[10:11] offset:1792 sc1
	global_load_dword v3, v16, s[10:11] offset:2048 sc1
	global_load_dword v4, v16, s[10:11] offset:2304 sc1
	global_load_dword v5, v16, s[10:11] offset:2560 sc1
	global_load_dword v6, v16, s[10:11] offset:2816 sc1
	global_load_dword v7, v16, s[10:11] offset:3072 sc1
	global_load_dword v8, v16, s[10:11] offset:3328 sc1
	global_load_dword v9, v16, s[10:11] offset:3584 sc1
	global_load_dword v10, v16, s[10:11] offset:3840 sc1
	global_load_dword v11, v16, s[2:3] sc1
	global_load_dword v12, v16, s[4:5] sc1
	global_load_dword v13, v16, s[6:7] sc1
	global_load_dword v14, v16, s[46:47] sc1
	s_mov_b64 s[50:51], -1
	s_mov_b64 s[52:53], -1
	s_waitcnt vmcnt(14)
	v_add_u32_e32 v17, v0, v15
	s_waitcnt vmcnt(13)
	v_add_u32_e32 v17, v17, v1
	s_waitcnt vmcnt(12)
	v_add_u32_e32 v17, v17, v2
	s_waitcnt vmcnt(11)
	v_add_u32_e32 v17, v17, v3
	s_waitcnt vmcnt(10)
	v_add_u32_e32 v17, v17, v4
	s_waitcnt vmcnt(9)
	v_add_u32_e32 v17, v17, v5
	s_waitcnt vmcnt(8)
	v_add_u32_e32 v17, v17, v6
	s_waitcnt vmcnt(7)
	v_add_u32_e32 v17, v17, v7
	s_waitcnt vmcnt(6)
	v_add_u32_e32 v17, v17, v8
	s_waitcnt vmcnt(5)
	v_add_u32_e32 v17, v17, v9
	s_waitcnt vmcnt(4)
	v_add_u32_e32 v17, v17, v10
	s_waitcnt vmcnt(3)
	v_add_u32_e32 v17, v17, v11
	s_waitcnt vmcnt(2)
	v_add_u32_e32 v17, v17, v12
	s_waitcnt vmcnt(1)
	v_add_u32_e32 v17, v17, v13
	s_waitcnt vmcnt(0)
	v_add_u32_e32 v17, v17, v14
	v_cmp_eq_u32_e32 vcc, s56, v17
	s_cbranch_vccnz .LBB0_654
	s_and_b32 s50, s57, 0xff
	s_cmp_eq_u32 s50, 0
	s_mov_b64 s[50:51], -1
	s_mov_b64 s[54:55], -1
	s_sleep 3
	s_cbranch_scc0 .LBB0_659
	global_load_dword v17, v16, s[10:11] offset:512 sc1
	s_waitcnt vmcnt(0)
	v_cmp_eq_u32_e32 vcc, 0, v17
	s_cbranch_vccnz .LBB0_661
	s_mov_b64 s[54:55], 0

; __device__ __forceinline__ unsigned xb_ld(unsigned* p)              { return __hip_atomic_load(p, __ATOMIC_RELAXED, __HIP_MEMORY_SCOPE_AGENT); }
; #define XB_SPIN(cond, bar) do { unsigned _sp = 0; while (cond) { __builtin_amdgcn_s_sleep(1); \
;     if ((++_sp & 255u) == 0u) { if (xb_ld(&(bar)[XB_TMO])) break; if (_sp > XB_SPIN_CAP) { atomicAdd(&(bar)[XB_TMO], 1u); break; } } } } while (0)
; __device__ __forceinline__ void xcd_barrier(const XcdBarrier& b, const int wv) {
;     ...
;             else XB_SPIN(xb_ld(&bar[XB_TOPGEN]) == tg, bar);
.LBB0_673:
	s_and_b32 s56, s60, 0xff
	s_mov_b64 s[54:55], -1
	s_cmp_lg_u32 s56, 0
	s_mov_b64 s[58:59], -1
	s_sleep 3
	s_cbranch_scc1 .LBB0_676
	global_load_dword v2, v0, s[10:11] offset:512 sc1
	s_waitcnt vmcnt(0)
	v_cmp_eq_u32_e32 vcc, 0, v2
	s_cbranch_vccnz .LBB0_678
	s_mov_b64 s[58:59], 0
	s_mov_b64 s[56:57], -1

; __device__ __forceinline__ unsigned xb_ld(unsigned* p)              { return __hip_atomic_load(p, __ATOMIC_RELAXED, __HIP_MEMORY_SCOPE_AGENT); }
; #define XB_SPIN(cond, bar) do { unsigned _sp = 0; while (cond) { __builtin_amdgcn_s_sleep(1); \
;     if ((++_sp & 255u) == 0u) { if (xb_ld(&(bar)[XB_TMO])) break; if (_sp > XB_SPIN_CAP) { atomicAdd(&(bar)[XB_TMO], 1u); break; } } } } while (0)
; __device__ __forceinline__ void xcd_barrier(const XcdBarrier& b, const int wv) {
;     ...
;             XB_SPIN(xb_ld(&bar[XB_XGEN(b.x)]) == gen, bar);
.LBB0_690:
	s_and_b32 s56, s62, 0xff
	s_cmp_lg_u32 s56, 0
	s_mov_b64 s[58:59], -1
	s_sleep 3
	s_cbranch_scc1 .LBB0_693
	global_load_dword v1, v0, s[46:47] sc1
	s_waitcnt vmcnt(0)
	v_cmp_eq_u32_e32 vcc, 0, v1
	s_cbranch_vccnz .LBB0_695
	s_mov_b64 s[58:59], 0
	s_mov_b64 s[56:57], -1

; __device__ __forceinline__ unsigned xb_ld(unsigned* p)              { return __hip_atomic_load(p, __ATOMIC_RELAXED, __HIP_MEMORY_SCOPE_AGENT); }
; __device__ __forceinline__ void xcd_barrier_complete(unsigned* bar, unsigned x, unsigned& nloc, unsigned& nx) {
;     const unsigned G = gridDim.x * gridDim.y * gridDim.z;
;     unsigned sum, cnt, mine, sp = 0u;
;     for (;;) {
;         sum = 0u; cnt = 0u; mine = 0u;
; #pragma unroll
;         for (unsigned j = 0; j < 16; ++j) { const unsigned c = xb_ld(&bar[XB_XCNT(j)]); sum += c; cnt += (c > 0u) ? 1u : 0u; mine = (j == x) ? c : mine; }
;         if (sum == G) break;
;         __builtin_amdgcn_s_sleep(1);
;         if ((++sp & 255u) == 0u) { if (xb_ld(&bar[XB_TMO])) break; if (sp > XB_SPIN_CAP) { atomicAdd(&bar[XB_TMO], 1u); break; } }
;     }
;     nloc = mine > 0u ? mine : 1u; nx = cnt > 0u ? cnt : 1u;
; }
.LBB0_1055:
	global_load_dword v15, v16, s[10:11] offset:1024 sc1
	s_waitcnt lgkmcnt(0)
	global_load_dword v0, v16, s[10:11] offset:1280 sc1
	global_load_dword v1, v16, s[10:11] offset:1536 sc1
	global_load_dword v2, v16, s[10:11] offset:1792 sc1
	global_load_dword v3, v16, s[10:11] offset:2048 sc1
	global_load_dword v4, v16, s[10:11] offset:2304 sc1
	global_load_dword v5, v16, s[10:11] offset:2560 sc1
	global_load_dword v6, v16, s[10:11] offset:2816 sc1
	global_load_dword v7, v16, s[10:11] offset:3072 sc1
	global_load_dword v8, v16, s[10:11] offset:3328 sc1
	global_load_dword v9, v16, s[10:11] offset:3584 sc1
	global_load_dword v10, v16, s[10:11] offset:3840 sc1
	global_load_dword v11, v16, s[4:5] sc1
	global_load_dword v12, v16, s[20:21] sc1
	global_load_dword v13, v16, s[36:37] sc1
	global_load_dword v14, v16, s[38:39] sc1
	s_mov_b64 s[40:41], -1
	s_mov_b64 s[42:43], -1
	s_waitcnt vmcnt(14)
	v_add_u32_e32 v17, v0, v15
	s_waitcnt vmcnt(13)
	v_add_u32_e32 v17, v17, v1
	s_waitcnt vmcnt(12)
	v_add_u32_e32 v17, v17, v2
	s_waitcnt vmcnt(11)
	v_add_u32_e32 v17, v17, v3
	s_waitcnt vmcnt(10)
	v_add_u32_e32 v17, v17, v4
	s_waitcnt vmcnt(9)
	v_add_u32_e32 v17, v17, v5
	s_waitcnt vmcnt(8)
	v_add_u32_e32 v17, v17, v6
	s_waitcnt vmcnt(7)
	v_add_u32_e32 v17, v17, v7
	s_waitcnt vmcnt(6)
	v_add_u32_e32 v17, v17, v8
	s_waitcnt vmcnt(5)
	v_add_u32_e32 v17, v17, v9
	s_waitcnt vmcnt(4)
	v_add_u32_e32 v17, v17, v10
	s_waitcnt vmcnt(3)
	v_add_u32_e32 v17, v17, v11
	s_waitcnt vmcnt(2)
	v_add_u32_e32 v17, v17, v12
	s_waitcnt vmcnt(1)
	v_add_u32_e32 v17, v17, v13
	s_waitcnt vmcnt(0)
	v_add_u32_e32 v17, v17, v14
	v_cmp_eq_u32_e32 vcc, s29, v17
	s_cbranch_vccnz .LBB0_1054
	s_and_b32 s40, s31, 0xff
	s_cmp_eq_u32 s40, 0
	s_mov_b64 s[40:41], -1
	s_mov_b64 s[46:47], -1
	s_sleep 3
	s_cbranch_scc0 .LBB0_1059
	global_load_dword v17, v16, s[10:11] offset:512 sc1
	s_waitcnt vmcnt(0)
	v_cmp_eq_u32_e32 vcc, 0, v17
	s_cbranch_vccnz .LBB0_1061
	s_mov_b64 s[46:47], 0

; __device__ __forceinline__ unsigned xb_ld(unsigned* p)              { return __hip_atomic_load(p, __ATOMIC_RELAXED, __HIP_MEMORY_SCOPE_AGENT); }
; #define XB_SPIN(cond, bar) do { unsigned _sp = 0; while (cond) { __builtin_amdgcn_s_sleep(1); \
;     if ((++_sp & 255u) == 0u) { if (xb_ld(&(bar)[XB_TMO])) break; if (_sp > XB_SPIN_CAP) { atomicAdd(&(bar)[XB_TMO], 1u); break; } } } } while (0)
; __device__ __forceinline__ void xcd_barrier(const XcdBarrier& b, const int wv) {
;     ...
;             else XB_SPIN(xb_ld(&bar[XB_TOPGEN]) == tg, bar);
.LBB0_1073:
	s_and_b32 s31, s29, 0xff
	s_mov_b64 s[46:47], -1
	s_cmp_lg_u32 s31, 0
	s_mov_b64 s[52:53], -1
	s_sleep 3
	s_cbranch_scc1 .LBB0_1076
	global_load_dword v2, v0, s[10:11] offset:512 sc1
	s_waitcnt vmcnt(0)
	v_cmp_eq_u32_e32 vcc, 0, v2
	s_cbranch_vccnz .LBB0_1078
	s_mov_b64 s[52:53], 0
	s_mov_b64 s[50:51], -1

; __device__ __forceinline__ unsigned xb_ld(unsigned* p)              { return __hip_atomic_load(p, __ATOMIC_RELAXED, __HIP_MEMORY_SCOPE_AGENT); }
; #define XB_SPIN(cond, bar) do { unsigned _sp = 0; while (cond) { __builtin_amdgcn_s_sleep(1); \
;     if ((++_sp & 255u) == 0u) { if (xb_ld(&(bar)[XB_TMO])) break; if (_sp > XB_SPIN_CAP) { atomicAdd(&(bar)[XB_TMO], 1u); break; } } } } while (0)
; __device__ __forceinline__ void xcd_barrier(const XcdBarrier& b, const int wv) {
;     ...
;             XB_SPIN(xb_ld(&bar[XB_XGEN(b.x)]) == gen, bar);
.LBB0_1090:
	s_and_b32 s31, s29, 0xff
	s_cmp_lg_u32 s31, 0
	s_mov_b64 s[52:53], -1
	s_sleep 3
	s_cbranch_scc1 .LBB0_1093
	global_load_dword v1, v0, s[38:39] sc1
	s_waitcnt vmcnt(0)
	v_cmp_eq_u32_e32 vcc, 0, v1
	s_cbranch_vccnz .LBB0_1095
	s_mov_b64 s[52:53], 0
	s_mov_b64 s[50:51], -1

; __device__ __forceinline__ unsigned xb_ld(unsigned* p)              { return __hip_atomic_load(p, __ATOMIC_RELAXED, __HIP_MEMORY_SCOPE_AGENT); }
; __device__ __forceinline__ void xcd_barrier_complete(unsigned* bar, unsigned x, unsigned& nloc, unsigned& nx) {
;     const unsigned G = gridDim.x * gridDim.y * gridDim.z;
;     unsigned sum, cnt, mine, sp = 0u;
;     for (;;) {
;         sum = 0u; cnt = 0u; mine = 0u;
; #pragma unroll
;         for (unsigned j = 0; j < 16; ++j) { const unsigned c = xb_ld(&bar[XB_XCNT(j)]); sum += c; cnt += (c > 0u) ? 1u : 0u; mine = (j == x) ? c : mine; }
;         if (sum == G) break;
;         __builtin_amdgcn_s_sleep(1);
;         if ((++sp & 255u) == 0u) { if (xb_ld(&bar[XB_TMO])) break; if (sp > XB_SPIN_CAP) { atomicAdd(&bar[XB_TMO], 1u); break; } }
;     }
;     nloc = mine > 0u ? mine : 1u; nx = cnt > 0u ? cnt : 1u;
; }
.LBB0_1204:
	global_load_dword v15, v16, s[10:11] offset:1024 sc1
	s_waitcnt lgkmcnt(0)
	global_load_dword v0, v16, s[10:11] offset:1280 sc1
	global_load_dword v1, v16, s[10:11] offset:1536 sc1
	global_load_dword v2, v16, s[10:11] offset:1792 sc1
	global_load_dword v3, v16, s[10:11] offset:2048 sc1
	global_load_dword v4, v16, s[10:11] offset:2304 sc1
	global_load_dword v5, v16, s[10:11] offset:2560 sc1
	global_load_dword v6, v16, s[10:11] offset:2816 sc1
	global_load_dword v7, v16, s[10:11] offset:3072 sc1
	global_load_dword v8, v16, s[10:11] offset:3328 sc1
	global_load_dword v9, v16, s[10:11] offset:3584 sc1
	global_load_dword v10, v16, s[10:11] offset:3840 sc1
	global_load_dword v11, v16, s[4:5] sc1
	global_load_dword v12, v16, s[6:7] sc1
	global_load_dword v13, v16, s[20:21] sc1
	global_load_dword v14, v16, s[22:23] sc1
	s_mov_b64 s[36:37], -1
	s_mov_b64 s[38:39], -1
	s_waitcnt vmcnt(14)
	v_add_u32_e32 v17, v0, v15
	s_waitcnt vmcnt(13)
	v_add_u32_e32 v17, v17, v1
	s_waitcnt vmcnt(12)
	v_add_u32_e32 v17, v17, v2
	s_waitcnt vmcnt(11)
	v_add_u32_e32 v17, v17, v3
	s_waitcnt vmcnt(10)
	v_add_u32_e32 v17, v17, v4
	s_waitcnt vmcnt(9)
	v_add_u32_e32 v17, v17, v5
	s_waitcnt vmcnt(8)
	v_add_u32_e32 v17, v17, v6
	s_waitcnt vmcnt(7)
	v_add_u32_e32 v17, v17, v7
	s_waitcnt vmcnt(6)
	v_add_u32_e32 v17, v17, v8
	s_waitcnt vmcnt(5)
	v_add_u32_e32 v17, v17, v9
	s_waitcnt vmcnt(4)
	v_add_u32_e32 v17, v17, v10
	s_waitcnt vmcnt(3)
	v_add_u32_e32 v17, v17, v11
	s_waitcnt vmcnt(2)
	v_add_u32_e32 v17, v17, v12
	s_waitcnt vmcnt(1)
	v_add_u32_e32 v17, v17, v13
	s_waitcnt vmcnt(0)
	v_add_u32_e32 v17, v17, v14
	v_cmp_eq_u32_e32 vcc, s29, v17
	s_cbranch_vccnz .LBB0_1203
	s_and_b32 s36, s31, 0xff
	s_cmp_eq_u32 s36, 0
	s_mov_b64 s[36:37], -1
	s_mov_b64 s[40:41], -1
	s_sleep 3
	s_cbranch_scc0 .LBB0_1208
	global_load_dword v17, v16, s[10:11] offset:512 sc1
	s_waitcnt vmcnt(0)
	v_cmp_eq_u32_e32 vcc, 0, v17
	s_cbranch_vccnz .LBB0_1210
	s_mov_b64 s[40:41], 0

; __device__ __forceinline__ unsigned xb_ld(unsigned* p)              { return __hip_atomic_load(p, __ATOMIC_RELAXED, __HIP_MEMORY_SCOPE_AGENT); }
; #define XB_SPIN(cond, bar) do { unsigned _sp = 0; while (cond) { __builtin_amdgcn_s_sleep(1); \
;     if ((++_sp & 255u) == 0u) { if (xb_ld(&(bar)[XB_TMO])) break; if (_sp > XB_SPIN_CAP) { atomicAdd(&(bar)[XB_TMO], 1u); break; } } } } while (0)
; __device__ __forceinline__ void xcd_barrier(const XcdBarrier& b, const int wv) {
;     ...
;             else XB_SPIN(xb_ld(&bar[XB_TOPGEN]) == tg, bar);
.LBB0_1222:
	s_and_b32 s31, s29, 0xff
	s_mov_b64 s[40:41], -1
	s_cmp_lg_u32 s31, 0
	s_mov_b64 s[44:45], -1
	s_sleep 3
	s_cbranch_scc1 .LBB0_1225
	global_load_dword v2, v0, s[10:11] offset:512 sc1
	s_waitcnt vmcnt(0)
	v_cmp_eq_u32_e32 vcc, 0, v2
	s_cbranch_vccnz .LBB0_1227
	s_mov_b64 s[44:45], 0
	s_mov_b64 s[42:43], -1

; __device__ __forceinline__ unsigned xb_ld(unsigned* p)              { return __hip_atomic_load(p, __ATOMIC_RELAXED, __HIP_MEMORY_SCOPE_AGENT); }
; #define XB_SPIN(cond, bar) do { unsigned _sp = 0; while (cond) { __builtin_amdgcn_s_sleep(1); \
;     if ((++_sp & 255u) == 0u) { if (xb_ld(&(bar)[XB_TMO])) break; if (_sp > XB_SPIN_CAP) { atomicAdd(&(bar)[XB_TMO], 1u); break; } } } } while (0)
; __device__ __forceinline__ void xcd_barrier(const XcdBarrier& b, const int wv) {
;     ...
;             XB_SPIN(xb_ld(&bar[XB_XGEN(b.x)]) == gen, bar);
.LBB0_1239:
	s_and_b32 s31, s29, 0xff
	s_cmp_lg_u32 s31, 0
	s_mov_b64 s[44:45], -1
	s_sleep 3
	s_cbranch_scc1 .LBB0_1242
	global_load_dword v1, v0, s[22:23] sc1
	s_waitcnt vmcnt(0)
	v_cmp_eq_u32_e32 vcc, 0, v1
	s_cbranch_vccnz .LBB0_1244
	s_mov_b64 s[44:45], 0
	s_mov_b64 s[42:43], -1

; __device__ __forceinline__ unsigned xb_ld(unsigned* p)              { return __hip_atomic_load(p, __ATOMIC_RELAXED, __HIP_MEMORY_SCOPE_AGENT); }
; __device__ __forceinline__ void xcd_barrier_complete(unsigned* bar, unsigned x, unsigned& nloc, unsigned& nx) {
;     const unsigned G = gridDim.x * gridDim.y * gridDim.z;
;     unsigned sum, cnt, mine, sp = 0u;
;     for (;;) {
;         sum = 0u; cnt = 0u; mine = 0u;
; #pragma unroll
;         for (unsigned j = 0; j < 16; ++j) { const unsigned c = xb_ld(&bar[XB_XCNT(j)]); sum += c; cnt += (c > 0u) ? 1u : 0u; mine = (j == x) ? c : mine; }
;         if (sum == G) break;
;         __builtin_amdgcn_s_sleep(1);
;         if ((++sp & 255u) == 0u) { if (xb_ld(&bar[XB_TMO])) break; if (sp > XB_SPIN_CAP) { atomicAdd(&bar[XB_TMO], 1u); break; } }
;     }
;     nloc = mine > 0u ? mine : 1u; nx = cnt > 0u ? cnt : 1u;
; }
.LBB0_1276:
	global_load_dword v15, v16, s[10:11] offset:1024 sc1
	s_waitcnt lgkmcnt(0)
	global_load_dword v0, v16, s[10:11] offset:1280 sc1
	global_load_dword v1, v16, s[10:11] offset:1536 sc1
	global_load_dword v2, v16, s[10:11] offset:1792 sc1
	global_load_dword v3, v16, s[10:11] offset:2048 sc1
	global_load_dword v4, v16, s[10:11] offset:2304 sc1
	global_load_dword v5, v16, s[10:11] offset:2560 sc1
	global_load_dword v6, v16, s[10:11] offset:2816 sc1
	global_load_dword v7, v16, s[10:11] offset:3072 sc1
	global_load_dword v8, v16, s[10:11] offset:3328 sc1
	global_load_dword v9, v16, s[10:11] offset:3584 sc1
	global_load_dword v10, v16, s[10:11] offset:3840 sc1
	global_load_dword v11, v16, s[4:5] sc1
	global_load_dword v12, v16, s[20:21] sc1
	global_load_dword v13, v16, s[22:23] sc1
	global_load_dword v14, v16, s[36:37] sc1
	s_mov_b64 s[38:39], -1
	s_mov_b64 s[40:41], -1
	s_waitcnt vmcnt(14)
	v_add_u32_e32 v17, v0, v15
	s_waitcnt vmcnt(13)
	v_add_u32_e32 v17, v17, v1
	s_waitcnt vmcnt(12)
	v_add_u32_e32 v17, v17, v2
	s_waitcnt vmcnt(11)
	v_add_u32_e32 v17, v17, v3
	s_waitcnt vmcnt(10)
	v_add_u32_e32 v17, v17, v4
	s_waitcnt vmcnt(9)
	v_add_u32_e32 v17, v17, v5
	s_waitcnt vmcnt(8)
	v_add_u32_e32 v17, v17, v6
	s_waitcnt vmcnt(7)
	v_add_u32_e32 v17, v17, v7
	s_waitcnt vmcnt(6)
	v_add_u32_e32 v17, v17, v8
	s_waitcnt vmcnt(5)
	v_add_u32_e32 v17, v17, v9
	s_waitcnt vmcnt(4)
	v_add_u32_e32 v17, v17, v10
	s_waitcnt vmcnt(3)
	v_add_u32_e32 v17, v17, v11
	s_waitcnt vmcnt(2)
	v_add_u32_e32 v17, v17, v12
	s_waitcnt vmcnt(1)
	v_add_u32_e32 v17, v17, v13
	s_waitcnt vmcnt(0)
	v_add_u32_e32 v17, v17, v14
	v_cmp_eq_u32_e32 vcc, s29, v17
	s_cbranch_vccnz .LBB0_1275
	s_and_b32 s38, s31, 0xff
	s_cmp_eq_u32 s38, 0
	s_mov_b64 s[38:39], -1
	s_mov_b64 s[42:43], -1
	s_sleep 3
	s_cbranch_scc0 .LBB0_1280
	global_load_dword v17, v16, s[10:11] offset:512 sc1
	s_waitcnt vmcnt(0)
	v_cmp_eq_u32_e32 vcc, 0, v17
	s_cbranch_vccnz .LBB0_1282
	s_mov_b64 s[42:43], 0

; __device__ __forceinline__ unsigned xb_ld(unsigned* p)              { return __hip_atomic_load(p, __ATOMIC_RELAXED, __HIP_MEMORY_SCOPE_AGENT); }
; #define XB_SPIN(cond, bar) do { unsigned _sp = 0; while (cond) { __builtin_amdgcn_s_sleep(1); \
;     if ((++_sp & 255u) == 0u) { if (xb_ld(&(bar)[XB_TMO])) break; if (_sp > XB_SPIN_CAP) { atomicAdd(&(bar)[XB_TMO], 1u); break; } } } } while (0)
; __device__ __forceinline__ void xcd_barrier(const XcdBarrier& b, const int wv) {
;     ...
;             else XB_SPIN(xb_ld(&bar[XB_TOPGEN]) == tg, bar);
.LBB0_1294:
	s_and_b32 s31, s29, 0xff
	s_mov_b64 s[42:43], -1
	s_cmp_lg_u32 s31, 0
	s_mov_b64 s[46:47], -1
	s_sleep 3
	s_cbranch_scc1 .LBB0_1297
	global_load_dword v2, v0, s[10:11] offset:512 sc1
	s_waitcnt vmcnt(0)
	v_cmp_eq_u32_e32 vcc, 0, v2
	s_cbranch_vccnz .LBB0_1299
	s_mov_b64 s[46:47], 0
	s_mov_b64 s[44:45], -1

; __device__ __forceinline__ unsigned xb_ld(unsigned* p)              { return __hip_atomic_load(p, __ATOMIC_RELAXED, __HIP_MEMORY_SCOPE_AGENT); }
; #define XB_SPIN(cond, bar) do { unsigned _sp = 0; while (cond) { __builtin_amdgcn_s_sleep(1); \
;     if ((++_sp & 255u) == 0u) { if (xb_ld(&(bar)[XB_TMO])) break; if (_sp > XB_SPIN_CAP) { atomicAdd(&(bar)[XB_TMO], 1u); break; } } } } while (0)
; __device__ __forceinline__ void xcd_barrier(const XcdBarrier& b, const int wv) {
;     ...
;             XB_SPIN(xb_ld(&bar[XB_XGEN(b.x)]) == gen, bar);
.LBB0_1311:
	s_and_b32 s31, s29, 0xff
	s_cmp_lg_u32 s31, 0
	s_mov_b64 s[46:47], -1
	s_sleep 3
	s_cbranch_scc1 .LBB0_1314
	global_load_dword v1, v0, s[36:37] sc1
	s_waitcnt vmcnt(0)
	v_cmp_eq_u32_e32 vcc, 0, v1
	s_cbranch_vccnz .LBB0_1316
	s_mov_b64 s[46:47], 0
	s_mov_b64 s[44:45], -1

; __device__ __forceinline__ unsigned xb_ld(unsigned* p)              { return __hip_atomic_load(p, __ATOMIC_RELAXED, __HIP_MEMORY_SCOPE_AGENT); }
; __device__ __forceinline__ void xcd_barrier_complete(unsigned* bar, unsigned x, unsigned& nloc, unsigned& nx) {
;     const unsigned G = gridDim.x * gridDim.y * gridDim.z;
;     unsigned sum, cnt, mine, sp = 0u;
;     for (;;) {
;         sum = 0u; cnt = 0u; mine = 0u;
; #pragma unroll
;         for (unsigned j = 0; j < 16; ++j) { const unsigned c = xb_ld(&bar[XB_XCNT(j)]); sum += c; cnt += (c > 0u) ? 1u : 0u; mine = (j == x) ? c : mine; }
;         if (sum == G) break;
;         __builtin_amdgcn_s_sleep(1);
;         if ((++sp & 255u) == 0u) { if (xb_ld(&bar[XB_TMO])) break; if (sp > XB_SPIN_CAP) { atomicAdd(&bar[XB_TMO], 1u); break; } }
;     }
;     nloc = mine > 0u ? mine : 1u; nx = cnt > 0u ? cnt : 1u;
; }
.LBB0_1333:
	global_load_dword v15, v16, s[10:11] offset:1024 sc1
	s_waitcnt lgkmcnt(0)
	global_load_dword v0, v16, s[10:11] offset:1280 sc1
	global_load_dword v1, v16, s[10:11] offset:1536 sc1
	global_load_dword v2, v16, s[10:11] offset:1792 sc1
	global_load_dword v3, v16, s[10:11] offset:2048 sc1
	global_load_dword v4, v16, s[10:11] offset:2304 sc1
	global_load_dword v5, v16, s[10:11] offset:2560 sc1
	global_load_dword v6, v16, s[10:11] offset:2816 sc1
	global_load_dword v7, v16, s[10:11] offset:3072 sc1
	global_load_dword v8, v16, s[10:11] offset:3328 sc1
	global_load_dword v9, v16, s[10:11] offset:3584 sc1
	global_load_dword v10, v16, s[10:11] offset:3840 sc1
	global_load_dword v11, v16, s[20:21] sc1
	global_load_dword v12, v16, s[22:23] sc1
	global_load_dword v13, v16, s[34:35] sc1
	global_load_dword v14, v16, s[36:37] sc1
	s_mov_b64 s[38:39], -1
	s_mov_b64 s[40:41], -1
	s_waitcnt vmcnt(14)
	v_add_u32_e32 v17, v0, v15
	s_waitcnt vmcnt(13)
	v_add_u32_e32 v17, v17, v1
	s_waitcnt vmcnt(12)
	v_add_u32_e32 v17, v17, v2
	s_waitcnt vmcnt(11)
	v_add_u32_e32 v17, v17, v3
	s_waitcnt vmcnt(10)
	v_add_u32_e32 v17, v17, v4
	s_waitcnt vmcnt(9)
	v_add_u32_e32 v17, v17, v5
	s_waitcnt vmcnt(8)
	v_add_u32_e32 v17, v17, v6
	s_waitcnt vmcnt(7)
	v_add_u32_e32 v17, v17, v7
	s_waitcnt vmcnt(6)
	v_add_u32_e32 v17, v17, v8
	s_waitcnt vmcnt(5)
	v_add_u32_e32 v17, v17, v9
	s_waitcnt vmcnt(4)
	v_add_u32_e32 v17, v17, v10
	s_waitcnt vmcnt(3)
	v_add_u32_e32 v17, v17, v11
	s_waitcnt vmcnt(2)
	v_add_u32_e32 v17, v17, v12
	s_waitcnt vmcnt(1)
	v_add_u32_e32 v17, v17, v13
	s_waitcnt vmcnt(0)
	v_add_u32_e32 v17, v17, v14
	v_cmp_eq_u32_e32 vcc, s29, v17
	s_cbranch_vccnz .LBB0_1332
	s_and_b32 s38, s31, 0xff
	s_cmp_eq_u32 s38, 0
	s_mov_b64 s[38:39], -1
	s_mov_b64 s[42:43], -1
	s_sleep 3
	s_cbranch_scc0 .LBB0_1337
	global_load_dword v17, v16, s[10:11] offset:512 sc1
	s_waitcnt vmcnt(0)
	v_cmp_eq_u32_e32 vcc, 0, v17
	s_cbranch_vccnz .LBB0_1339
	s_mov_b64 s[42:43], 0

; __device__ __forceinline__ unsigned xb_ld(unsigned* p)              { return __hip_atomic_load(p, __ATOMIC_RELAXED, __HIP_MEMORY_SCOPE_AGENT); }
; __device__ __forceinline__ void xcd_barrier_complete(unsigned* bar, unsigned x, unsigned& nloc, unsigned& nx) {
;     const unsigned G = gridDim.x * gridDim.y * gridDim.z;
;     unsigned sum, cnt, mine, sp = 0u;
;     for (;;) {
;         sum = 0u; cnt = 0u; mine = 0u;
; #pragma unroll
;         for (unsigned j = 0; j < 16; ++j) { const unsigned c = xb_ld(&bar[XB_XCNT(j)]); sum += c; cnt += (c > 0u) ? 1u : 0u; mine = (j == x) ? c : mine; }
;         if (sum == G) break;
;         __builtin_amdgcn_s_sleep(1);
;         if ((++sp & 255u) == 0u) { if (xb_ld(&bar[XB_TMO])) break; if (sp > XB_SPIN_CAP) { atomicAdd(&bar[XB_TMO], 1u); break; } }
;     }
;     nloc = mine > 0u ? mine : 1u; nx = cnt > 0u ? cnt : 1u;
; }
.LBB0_1402:
	global_load_dword v15, v16, s[10:11] offset:1024 sc1
	s_waitcnt lgkmcnt(0)
	global_load_dword v0, v16, s[10:11] offset:1280 sc1
	global_load_dword v1, v16, s[10:11] offset:1536 sc1
	global_load_dword v2, v16, s[10:11] offset:1792 sc1
	global_load_dword v3, v16, s[10:11] offset:2048 sc1
	global_load_dword v4, v16, s[10:11] offset:2304 sc1
	global_load_dword v5, v16, s[10:11] offset:2560 sc1
	global_load_dword v6, v16, s[10:11] offset:2816 sc1
	global_load_dword v7, v16, s[10:11] offset:3072 sc1
	global_load_dword v8, v16, s[10:11] offset:3328 sc1
	global_load_dword v9, v16, s[10:11] offset:3584 sc1
	global_load_dword v10, v16, s[10:11] offset:3840 sc1
	global_load_dword v11, v16, s[16:17] sc1
	global_load_dword v12, v16, s[18:19] sc1
	global_load_dword v13, v16, s[20:21] sc1
	global_load_dword v14, v16, s[22:23] sc1
	s_mov_b64 s[34:35], -1
	s_mov_b64 s[36:37], -1
	s_waitcnt vmcnt(14)
	v_add_u32_e32 v17, v0, v15
	s_waitcnt vmcnt(13)
	v_add_u32_e32 v17, v17, v1
	s_waitcnt vmcnt(12)
	v_add_u32_e32 v17, v17, v2
	s_waitcnt vmcnt(11)
	v_add_u32_e32 v17, v17, v3
	s_waitcnt vmcnt(10)
	v_add_u32_e32 v17, v17, v4
	s_waitcnt vmcnt(9)
	v_add_u32_e32 v17, v17, v5
	s_waitcnt vmcnt(8)
	v_add_u32_e32 v17, v17, v6
	s_waitcnt vmcnt(7)
	v_add_u32_e32 v17, v17, v7
	s_waitcnt vmcnt(6)
	v_add_u32_e32 v17, v17, v8
	s_waitcnt vmcnt(5)
	v_add_u32_e32 v17, v17, v9
	s_waitcnt vmcnt(4)
	v_add_u32_e32 v17, v17, v10
	s_waitcnt vmcnt(3)
	v_add_u32_e32 v17, v17, v11
	s_waitcnt vmcnt(2)
	v_add_u32_e32 v17, v17, v12
	s_waitcnt vmcnt(1)
	v_add_u32_e32 v17, v17, v13
	s_waitcnt vmcnt(0)
	v_add_u32_e32 v17, v17, v14
	v_cmp_eq_u32_e32 vcc, s29, v17
	s_cbranch_vccnz .LBB0_1401
	s_and_b32 s34, s31, 0xff
	s_cmp_eq_u32 s34, 0
	s_mov_b64 s[34:35], -1
	s_mov_b64 s[38:39], -1
	s_sleep 3
	s_cbranch_scc0 .LBB0_1406
	global_load_dword v17, v16, s[10:11] offset:512 sc1
	s_waitcnt vmcnt(0)
	v_cmp_eq_u32_e32 vcc, 0, v17
	s_cbranch_vccnz .LBB0_1408
	s_mov_b64 s[38:39], 0

; __device__ __forceinline__ unsigned xb_ld(unsigned* p)              { return __hip_atomic_load(p, __ATOMIC_RELAXED, __HIP_MEMORY_SCOPE_AGENT); }
; #define XB_SPIN(cond, bar) do { unsigned _sp = 0; while (cond) { __builtin_amdgcn_s_sleep(1); \
;     if ((++_sp & 255u) == 0u) { if (xb_ld(&(bar)[XB_TMO])) break; if (_sp > XB_SPIN_CAP) { atomicAdd(&(bar)[XB_TMO], 1u); break; } } } } while (0)
; __device__ __forceinline__ void xcd_barrier(const XcdBarrier& b, const int wv) {
;     ...
;             XB_SPIN(xb_ld(&bar[XB_XGEN(b.x)]) == gen, bar);
.LBB0_1437:
	s_and_b32 s31, s29, 0xff
	s_cmp_lg_u32 s31, 0
	s_mov_b64 s[42:43], -1
	s_sleep 3
	s_cbranch_scc1 .LBB0_1440
	global_load_dword v1, v0, s[22:23] sc1
	s_waitcnt vmcnt(0)
	v_cmp_eq_u32_e32 vcc, 0, v1
	s_cbranch_vccnz .LBB0_1442
	s_mov_b64 s[42:43], 0
	s_mov_b64 s[40:41], -1

; __device__ __forceinline__ unsigned xb_ld(unsigned* p)              { return __hip_atomic_load(p, __ATOMIC_RELAXED, __HIP_MEMORY_SCOPE_AGENT); }
; __device__ __forceinline__ void xcd_barrier_complete(unsigned* bar, unsigned x, unsigned& nloc, unsigned& nx) {
;     const unsigned G = gridDim.x * gridDim.y * gridDim.z;
;     unsigned sum, cnt, mine, sp = 0u;
;     for (;;) {
;         sum = 0u; cnt = 0u; mine = 0u;
; #pragma unroll
;         for (unsigned j = 0; j < 16; ++j) { const unsigned c = xb_ld(&bar[XB_XCNT(j)]); sum += c; cnt += (c > 0u) ? 1u : 0u; mine = (j == x) ? c : mine; }
;         if (sum == G) break;
;         __builtin_amdgcn_s_sleep(1);
;         if ((++sp & 255u) == 0u) { if (xb_ld(&bar[XB_TMO])) break; if (sp > XB_SPIN_CAP) { atomicAdd(&bar[XB_TMO], 1u); break; } }
;     }
;     nloc = mine > 0u ? mine : 1u; nx = cnt > 0u ? cnt : 1u;
; }
.LBB0_1493:
	global_load_dword v15, v16, s[10:11] offset:1024 sc1
	s_waitcnt lgkmcnt(0)
	global_load_dword v0, v16, s[10:11] offset:1280 sc1
	global_load_dword v1, v16, s[10:11] offset:1536 sc1
	global_load_dword v2, v16, s[10:11] offset:1792 sc1
	global_load_dword v3, v16, s[10:11] offset:2048 sc1
	global_load_dword v4, v16, s[10:11] offset:2304 sc1
	global_load_dword v5, v16, s[10:11] offset:2560 sc1
	global_load_dword v6, v16, s[10:11] offset:2816 sc1
	global_load_dword v7, v16, s[10:11] offset:3072 sc1
	global_load_dword v8, v16, s[10:11] offset:3328 sc1
	global_load_dword v9, v16, s[10:11] offset:3584 sc1
	global_load_dword v10, v16, s[10:11] offset:3840 sc1
	global_load_dword v11, v16, s[4:5] sc1
	global_load_dword v12, v16, s[6:7] sc1
	global_load_dword v13, v16, s[8:9] sc1
	global_load_dword v14, v16, s[12:13] sc1
	s_mov_b64 s[14:15], -1
	s_mov_b64 s[16:17], -1
	s_waitcnt vmcnt(14)
	v_add_u32_e32 v17, v0, v15
	s_waitcnt vmcnt(13)
	v_add_u32_e32 v17, v17, v1
	s_waitcnt vmcnt(12)
	v_add_u32_e32 v17, v17, v2
	s_waitcnt vmcnt(11)
	v_add_u32_e32 v17, v17, v3
	s_waitcnt vmcnt(10)
	v_add_u32_e32 v17, v17, v4
	s_waitcnt vmcnt(9)
	v_add_u32_e32 v17, v17, v5
	s_waitcnt vmcnt(8)
	v_add_u32_e32 v17, v17, v6
	s_waitcnt vmcnt(7)
	v_add_u32_e32 v17, v17, v7
	s_waitcnt vmcnt(6)
	v_add_u32_e32 v17, v17, v8
	s_waitcnt vmcnt(5)
	v_add_u32_e32 v17, v17, v9
	s_waitcnt vmcnt(4)
	v_add_u32_e32 v17, v17, v10
	s_waitcnt vmcnt(3)
	v_add_u32_e32 v17, v17, v11
	s_waitcnt vmcnt(2)
	v_add_u32_e32 v17, v17, v12
	s_waitcnt vmcnt(1)
	v_add_u32_e32 v17, v17, v13
	s_waitcnt vmcnt(0)
	v_add_u32_e32 v17, v17, v14
	v_cmp_eq_u32_e32 vcc, s20, v17
	s_cbranch_vccnz .LBB0_1492
	s_and_b32 s14, s21, 0xff
	s_cmp_eq_u32 s14, 0
	s_mov_b64 s[14:15], -1
	s_mov_b64 s[18:19], -1
	s_sleep 3
	s_cbranch_scc0 .LBB0_1497
	global_load_dword v17, v16, s[10:11] offset:512 sc1
	s_waitcnt vmcnt(0)
	v_cmp_eq_u32_e32 vcc, 0, v17
	s_cbranch_vccnz .LBB0_1499
	s_mov_b64 s[18:19], 0

; __device__ __forceinline__ unsigned xb_ld(unsigned* p)              { return __hip_atomic_load(p, __ATOMIC_RELAXED, __HIP_MEMORY_SCOPE_AGENT); }
; #define XB_SPIN(cond, bar) do { unsigned _sp = 0; while (cond) { __builtin_amdgcn_s_sleep(1); \
;     if ((++_sp & 255u) == 0u) { if (xb_ld(&(bar)[XB_TMO])) break; if (_sp > XB_SPIN_CAP) { atomicAdd(&(bar)[XB_TMO], 1u); break; } } } } while (0)
; __device__ __forceinline__ void xcd_barrier(const XcdBarrier& b, const int wv) {
;     ...
;             else XB_SPIN(xb_ld(&bar[XB_TOPGEN]) == tg, bar);
.LBB0_1511:
	s_and_b32 s20, s29, 0xff
	s_mov_b64 s[18:19], -1
	s_cmp_lg_u32 s20, 0
	s_mov_b64 s[22:23], -1
	s_sleep 3
	s_cbranch_scc1 .LBB0_1514
	global_load_dword v2, v0, s[10:11] offset:512 sc1
	s_waitcnt vmcnt(0)
	v_cmp_eq_u32_e32 vcc, 0, v2
	s_cbranch_vccnz .LBB0_1516
	s_mov_b64 s[22:23], 0
	s_mov_b64 s[20:21], -1

; __device__ __forceinline__ unsigned xb_ld(unsigned* p)              { return __hip_atomic_load(p, __ATOMIC_RELAXED, __HIP_MEMORY_SCOPE_AGENT); }
; #define XB_SPIN(cond, bar) do { unsigned _sp = 0; while (cond) { __builtin_amdgcn_s_sleep(1); \
;     if ((++_sp & 255u) == 0u) { if (xb_ld(&(bar)[XB_TMO])) break; if (_sp > XB_SPIN_CAP) { atomicAdd(&(bar)[XB_TMO], 1u); break; } } } } while (0)
; __device__ __forceinline__ void xcd_barrier(const XcdBarrier& b, const int wv) {
;     ...
;             XB_SPIN(xb_ld(&bar[XB_XGEN(b.x)]) == gen, bar);
.LBB0_1528:
	s_and_b32 s20, s29, 0xff
	s_cmp_lg_u32 s20, 0
	s_mov_b64 s[22:23], -1
	s_sleep 3
	s_cbranch_scc1 .LBB0_1531
	global_load_dword v1, v0, s[12:13] sc1
	s_waitcnt vmcnt(0)
	v_cmp_eq_u32_e32 vcc, 0, v1
	s_cbranch_vccnz .LBB0_1533
	s_mov_b64 s[22:23], 0
	s_mov_b64 s[20:21], -1
